# P4 copies: waves 1..7 issue their first two items' loads inside grid barrier 4 (kernel inputs, no dependency), wave 0 after it
# baseline (speedup 1.0000x reference)
.LBB0_551:
	s_waitcnt vmcnt(0)
	s_barrier
	s_cmp_eq_u32 s91, 0
	s_cbranch_scc1 .Lp4_pre_skip
	v_mbcnt_lo_u32_b32 v176, -1, 0
	v_mbcnt_hi_u32_b32 v176, -1, v176
	s_load_dwordx2 s[40:41], s[0:1], 0x70
	s_load_dwordx4 s[60:63], s[0:1], 0x78
	s_lshr_b32 s77, s91, 2
	s_lshl_b32 s77, s77, 2
	s_add_i32 s77, s77, s91
	s_lshl_b32 s77, s77, 16
	v_lshrrev_b32_e32 v196, 3, v176
	v_and_b32_e32 v197, 7, v176
	v_mul_u32_u24_e32 v195, 0x58000, v196
	v_lshl_add_u32 v195, v197, 4, v195
	v_lshlrev_b32_e32 v199, 6, v196
	v_lshl_add_u32 v198, v197, 3, v196
	v_lshlrev_b32_e32 v198, 2, v198
	v_lshlrev_b32_e32 v196, 13, v196
	v_lshl_add_u32 v196, v197, 4, v196
	v_add_u32_e32 v197, 0x1000, v196
	v_mov_b32_e32 v192, 0x44800000
	v_mov_b32_e32 v193, 0x43e00000
	v_mov_b32_e32 v194, 0xc3e00000
	s_waitcnt lgkmcnt(0)
	s_mov_b32 s44, s2
	s_cmpk_ge_u32 s44, 0x160
	s_cselect_b32 s45, 1, 0
	s_mul_i32 s67, s45, 0x160
	s_sub_i32 s44, s44, s67
	s_mul_i32 s67, s44, 2979
	s_lshr_b32 s67, s67, 16
	s_mul_i32 s69, s67, 22
	s_sub_i32 s69, s44, s69
	s_lshl_b32 s67, s67, 7
	s_cmp_eq_u32 s45, 0
	s_cselect_b32 s20, s60, s62
	s_cselect_b32 s21, s61, s63
	s_mul_i32 s76, s67, 0x5800
	s_lshl_b32 s44, s69, 10
	s_add_i32 s76, s76, s44
	s_lshl_b32 s44, s91, 7
	s_add_i32 s76, s76, s44
	s_add_u32 s20, s20, s76
	s_addc_u32 s21, s21, 0
	s_lshl_b32 s44, s67, 2
	s_add_u32 s34, s40, s44
	s_addc_u32 s35, s41, 0
	s_lshl_b32 s44, s69, 20
	s_lshl_b32 s45, s45, 18
	s_add_i32 s44, s44, s45
	s_add_i32 s44, s44, s67
	s_add_i32 s44, s44, s77
	s_add_u32 s26, s50, s44
	s_addc_u32 s27, s51, 0
	s_add_u32 s26, s26, 0x6300000
	s_addc_u32 s27, s27, 0
	s_add_i32 s44, s2, 256
	s_cmpk_ge_u32 s44, 0x160
	s_cselect_b32 s45, 1, 0
	s_mul_i32 s67, s45, 0x160
	s_sub_i32 s44, s44, s67
	s_mul_i32 s67, s44, 2979
	s_lshr_b32 s67, s67, 16
	s_mul_i32 s69, s67, 22
	s_sub_i32 s69, s44, s69
	s_lshl_b32 s67, s67, 7
	s_cmp_eq_u32 s45, 0
	s_cselect_b32 s22, s60, s62
	s_cselect_b32 s23, s61, s63
	s_mul_i32 s76, s67, 0x5800
	s_lshl_b32 s44, s69, 10
	s_add_i32 s76, s76, s44
	s_lshl_b32 s44, s91, 7
	s_add_i32 s76, s76, s44
	s_add_u32 s22, s22, s76
	s_addc_u32 s23, s23, 0
	s_lshl_b32 s44, s67, 2
	s_add_u32 s36, s40, s44
	s_addc_u32 s37, s41, 0
	s_lshl_b32 s44, s69, 20
	s_lshl_b32 s45, s45, 18
	s_add_i32 s44, s44, s45
	s_add_i32 s44, s44, s67
	s_add_i32 s44, s44, s77
	s_add_u32 s28, s50, s44
	s_addc_u32 s29, s51, 0
	s_add_u32 s28, s28, 0x6300000
	s_addc_u32 s29, s29, 0
	global_load_dwordx4 v[64:67], v199, s[34:35] offset:0
	global_load_dwordx4 v[68:71], v199, s[34:35] offset:16
	global_load_dwordx4 v[72:75], v199, s[34:35] offset:32
	global_load_dwordx4 v[76:79], v199, s[34:35] offset:48
	global_load_dwordx4 v[0:3], v195, s[20:21] nt
	s_add_u32 s20, s20, 0x5800
	s_addc_u32 s21, s21, 0
	global_load_dwordx4 v[4:7], v195, s[20:21] nt
	s_add_u32 s20, s20, 0x5800
	s_addc_u32 s21, s21, 0
	global_load_dwordx4 v[8:11], v195, s[20:21] nt
	s_add_u32 s20, s20, 0x5800
	s_addc_u32 s21, s21, 0
	global_load_dwordx4 v[12:15], v195, s[20:21] nt
	s_add_u32 s20, s20, 0x5800
	s_addc_u32 s21, s21, 0
	global_load_dwordx4 v[16:19], v195, s[20:21] nt
	s_add_u32 s20, s20, 0x5800
	s_addc_u32 s21, s21, 0
	global_load_dwordx4 v[20:23], v195, s[20:21] nt
	s_add_u32 s20, s20, 0x5800
	s_addc_u32 s21, s21, 0
	global_load_dwordx4 v[24:27], v195, s[20:21] nt
	s_add_u32 s20, s20, 0x5800
	s_addc_u32 s21, s21, 0
	global_load_dwordx4 v[28:31], v195, s[20:21] nt
	s_add_u32 s20, s20, 0x5800
	s_addc_u32 s21, s21, 0
	global_load_dwordx4 v[32:35], v195, s[20:21] nt
	s_add_u32 s20, s20, 0x5800
	s_addc_u32 s21, s21, 0
	global_load_dwordx4 v[36:39], v195, s[20:21] nt
	s_add_u32 s20, s20, 0x5800
	s_addc_u32 s21, s21, 0
	global_load_dwordx4 v[40:43], v195, s[20:21] nt
	s_add_u32 s20, s20, 0x5800
	s_addc_u32 s21, s21, 0
	global_load_dwordx4 v[44:47], v195, s[20:21] nt
	s_add_u32 s20, s20, 0x5800
	s_addc_u32 s21, s21, 0
	global_load_dwordx4 v[48:51], v195, s[20:21] nt
	s_add_u32 s20, s20, 0x5800
	s_addc_u32 s21, s21, 0
	global_load_dwordx4 v[52:55], v195, s[20:21] nt
	s_add_u32 s20, s20, 0x5800
	s_addc_u32 s21, s21, 0
	global_load_dwordx4 v[56:59], v195, s[20:21] nt
	s_add_u32 s20, s20, 0x5800
	s_addc_u32 s21, s21, 0
	global_load_dwordx4 v[60:63], v195, s[20:21] nt
	global_load_dwordx4 v[144:147], v199, s[36:37] offset:0
	global_load_dwordx4 v[148:151], v199, s[36:37] offset:16
	global_load_dwordx4 v[152:155], v199, s[36:37] offset:32
	global_load_dwordx4 v[156:159], v199, s[36:37] offset:48
	global_load_dwordx4 v[80:83], v195, s[22:23] nt
	s_add_u32 s22, s22, 0x5800
	s_addc_u32 s23, s23, 0
	global_load_dwordx4 v[84:87], v195, s[22:23] nt
	s_add_u32 s22, s22, 0x5800
	s_addc_u32 s23, s23, 0
	global_load_dwordx4 v[88:91], v195, s[22:23] nt
	s_add_u32 s22, s22, 0x5800
	s_addc_u32 s23, s23, 0
	global_load_dwordx4 v[92:95], v195, s[22:23] nt
	s_add_u32 s22, s22, 0x5800
	s_addc_u32 s23, s23, 0
	global_load_dwordx4 v[96:99], v195, s[22:23] nt
	s_add_u32 s22, s22, 0x5800
	s_addc_u32 s23, s23, 0
	global_load_dwordx4 v[100:103], v195, s[22:23] nt
	s_add_u32 s22, s22, 0x5800
	s_addc_u32 s23, s23, 0
	global_load_dwordx4 v[104:107], v195, s[22:23] nt
	s_add_u32 s22, s22, 0x5800
	s_addc_u32 s23, s23, 0
	global_load_dwordx4 v[108:111], v195, s[22:23] nt
	s_add_u32 s22, s22, 0x5800
	s_addc_u32 s23, s23, 0
	global_load_dwordx4 v[112:115], v195, s[22:23] nt
	s_add_u32 s22, s22, 0x5800
	s_addc_u32 s23, s23, 0
	global_load_dwordx4 v[116:119], v195, s[22:23] nt
	s_add_u32 s22, s22, 0x5800
	s_addc_u32 s23, s23, 0
	global_load_dwordx4 v[120:123], v195, s[22:23] nt
	s_add_u32 s22, s22, 0x5800
	s_addc_u32 s23, s23, 0
	global_load_dwordx4 v[124:127], v195, s[22:23] nt
	s_add_u32 s22, s22, 0x5800
	s_addc_u32 s23, s23, 0
	global_load_dwordx4 v[128:131], v195, s[22:23] nt
	s_add_u32 s22, s22, 0x5800
	s_addc_u32 s23, s23, 0
	global_load_dwordx4 v[132:135], v195, s[22:23] nt
	s_add_u32 s22, s22, 0x5800
	s_addc_u32 s23, s23, 0
	global_load_dwordx4 v[136:139], v195, s[22:23] nt
	s_add_u32 s22, s22, 0x5800
	s_addc_u32 s23, s23, 0
	global_load_dwordx4 v[140:143], v195, s[22:23] nt
.Lp4_pre_skip:
	s_and_saveexec_b64 s[6:7], s[8:9]
	s_cbranch_execz .LBB0_603
	s_add_i32 s8, 0, 0x23fc0
	v_mov_b32_e32 v0, s8
	s_waitcnt vmcnt(0) expcnt(0) lgkmcnt(0)
	ds_read_b32 v2, v0
	s_add_i32 s8, 0, 0x23fc4
	v_mov_b32_e32 v0, s8
	ds_read_b32 v0, v0
	s_waitcnt lgkmcnt(1)
	v_cmp_ne_u32_e32 vcc, 0, v2
	s_cbranch_vccnz .LBB0_567
	s_load_dword s8, s[0:1], 0xc8
	s_mov_b32 s60, 1
	v_mov_b32_e32 v16, 0
	s_waitcnt lgkmcnt(0)
	s_mul_i32 s13, s47, s8
	s_add_u32 s8, s50, 0x80200
	s_addc_u32 s9, s51, 0
	s_add_u32 s10, s50, 0x80400
	s_addc_u32 s11, s51, 0
	s_add_u32 s14, s50, 0x80500
	s_addc_u32 s15, s51, 0
	s_add_u32 s16, s50, 0x80600
	s_addc_u32 s17, s51, 0
	s_add_u32 s18, s50, 0x80700
	s_addc_u32 s19, s51, 0
	s_add_u32 s20, s50, 0x80800
	s_addc_u32 s21, s51, 0
	s_add_u32 s22, s50, 0x80900
	s_addc_u32 s23, s51, 0
	s_add_u32 s24, s50, 0x80a00
	s_addc_u32 s25, s51, 0
	s_add_u32 s26, s50, 0x80b00
	s_addc_u32 s27, s51, 0
	s_add_u32 s28, s50, 0x80c00
	s_addc_u32 s29, s51, 0
	s_add_u32 s30, s50, 0x80d00
	s_addc_u32 s31, s51, 0
	s_add_u32 s34, s50, 0x80e00
	s_addc_u32 s35, s51, 0
	s_add_u32 s36, s50, 0x80f00
	s_addc_u32 s37, s51, 0
	s_add_u32 s38, s50, 0x81000
	s_addc_u32 s39, s51, 0
	s_add_u32 s40, s50, 0x81100
	s_addc_u32 s41, s51, 0
	s_add_u32 s44, s50, 0x81200
	s_addc_u32 s45, s51, 0
	s_add_u32 s74, s50, 0x81300
	s_mul_i32 s13, s13, s46
	s_addc_u32 s75, s51, 0
	s_branch .LBB0_555

.Lp4_copy_entry:
	s_cmp_lg_u32 s91, 0
	s_cbranch_scc1 .Lp4_copy_main
	v_mbcnt_lo_u32_b32 v176, -1, 0
	v_mbcnt_hi_u32_b32 v176, -1, v176
	s_load_dwordx2 s[40:41], s[0:1], 0x70
	s_load_dwordx4 s[60:63], s[0:1], 0x78
	s_lshr_b32 s77, s91, 2
	s_lshl_b32 s77, s77, 2
	s_add_i32 s77, s77, s91
	s_lshl_b32 s77, s77, 16
	v_lshrrev_b32_e32 v196, 3, v176
	v_and_b32_e32 v197, 7, v176
	v_mul_u32_u24_e32 v195, 0x58000, v196
	v_lshl_add_u32 v195, v197, 4, v195
	v_lshlrev_b32_e32 v199, 6, v196
	v_lshl_add_u32 v198, v197, 3, v196
	v_lshlrev_b32_e32 v198, 2, v198
	v_lshlrev_b32_e32 v196, 13, v196
	v_lshl_add_u32 v196, v197, 4, v196
	v_add_u32_e32 v197, 0x1000, v196
	v_mov_b32_e32 v192, 0x44800000
	v_mov_b32_e32 v193, 0x43e00000
	v_mov_b32_e32 v194, 0xc3e00000
	s_waitcnt lgkmcnt(0)
	s_mov_b32 s44, s2
	s_cmpk_ge_u32 s44, 0x160
	s_cselect_b32 s45, 1, 0
	s_mul_i32 s67, s45, 0x160
	s_sub_i32 s44, s44, s67
	s_mul_i32 s67, s44, 2979
	s_lshr_b32 s67, s67, 16
	s_mul_i32 s69, s67, 22
	s_sub_i32 s69, s44, s69
	s_lshl_b32 s67, s67, 7
	s_cmp_eq_u32 s45, 0
	s_cselect_b32 s20, s60, s62
	s_cselect_b32 s21, s61, s63
	s_mul_i32 s76, s67, 0x5800
	s_lshl_b32 s44, s69, 10
	s_add_i32 s76, s76, s44
	s_lshl_b32 s44, s91, 7
	s_add_i32 s76, s76, s44
	s_add_u32 s20, s20, s76
	s_addc_u32 s21, s21, 0
	s_lshl_b32 s44, s67, 2
	s_add_u32 s34, s40, s44
	s_addc_u32 s35, s41, 0
	s_lshl_b32 s44, s69, 20
	s_lshl_b32 s45, s45, 18
	s_add_i32 s44, s44, s45
	s_add_i32 s44, s44, s67
	s_add_i32 s44, s44, s77
	s_add_u32 s26, s50, s44
	s_addc_u32 s27, s51, 0
	s_add_u32 s26, s26, 0x6300000
	s_addc_u32 s27, s27, 0
	s_add_i32 s44, s2, 256
	s_cmpk_ge_u32 s44, 0x160
	s_cselect_b32 s45, 1, 0
	s_mul_i32 s67, s45, 0x160
	s_sub_i32 s44, s44, s67
	s_mul_i32 s67, s44, 2979
	s_lshr_b32 s67, s67, 16
	s_mul_i32 s69, s67, 22
	s_sub_i32 s69, s44, s69
	s_lshl_b32 s67, s67, 7
	s_cmp_eq_u32 s45, 0
	s_cselect_b32 s22, s60, s62
	s_cselect_b32 s23, s61, s63
	s_mul_i32 s76, s67, 0x5800
	s_lshl_b32 s44, s69, 10
	s_add_i32 s76, s76, s44
	s_lshl_b32 s44, s91, 7
	s_add_i32 s76, s76, s44
	s_add_u32 s22, s22, s76
	s_addc_u32 s23, s23, 0
	s_lshl_b32 s44, s67, 2
	s_add_u32 s36, s40, s44
	s_addc_u32 s37, s41, 0
	s_lshl_b32 s44, s69, 20
	s_lshl_b32 s45, s45, 18
	s_add_i32 s44, s44, s45
	s_add_i32 s44, s44, s67
	s_add_i32 s44, s44, s77
	s_add_u32 s28, s50, s44
	s_addc_u32 s29, s51, 0
	s_add_u32 s28, s28, 0x6300000
	s_addc_u32 s29, s29, 0
	global_load_dwordx4 v[64:67], v199, s[34:35] offset:0
	global_load_dwordx4 v[68:71], v199, s[34:35] offset:16
	global_load_dwordx4 v[72:75], v199, s[34:35] offset:32
	global_load_dwordx4 v[76:79], v199, s[34:35] offset:48
	global_load_dwordx4 v[0:3], v195, s[20:21] nt
	s_add_u32 s20, s20, 0x5800
	s_addc_u32 s21, s21, 0
	global_load_dwordx4 v[4:7], v195, s[20:21] nt
	s_add_u32 s20, s20, 0x5800
	s_addc_u32 s21, s21, 0
	global_load_dwordx4 v[8:11], v195, s[20:21] nt
	s_add_u32 s20, s20, 0x5800
	s_addc_u32 s21, s21, 0
	global_load_dwordx4 v[12:15], v195, s[20:21] nt
	s_add_u32 s20, s20, 0x5800
	s_addc_u32 s21, s21, 0
	global_load_dwordx4 v[16:19], v195, s[20:21] nt
	s_add_u32 s20, s20, 0x5800
	s_addc_u32 s21, s21, 0
	global_load_dwordx4 v[20:23], v195, s[20:21] nt
	s_add_u32 s20, s20, 0x5800
	s_addc_u32 s21, s21, 0
	global_load_dwordx4 v[24:27], v195, s[20:21] nt
	s_add_u32 s20, s20, 0x5800
	s_addc_u32 s21, s21, 0
	global_load_dwordx4 v[28:31], v195, s[20:21] nt
	s_add_u32 s20, s20, 0x5800
	s_addc_u32 s21, s21, 0
	global_load_dwordx4 v[32:35], v195, s[20:21] nt
	s_add_u32 s20, s20, 0x5800
	s_addc_u32 s21, s21, 0
	global_load_dwordx4 v[36:39], v195, s[20:21] nt
	s_add_u32 s20, s20, 0x5800
	s_addc_u32 s21, s21, 0
	global_load_dwordx4 v[40:43], v195, s[20:21] nt
	s_add_u32 s20, s20, 0x5800
	s_addc_u32 s21, s21, 0
	global_load_dwordx4 v[44:47], v195, s[20:21] nt
	s_add_u32 s20, s20, 0x5800
	s_addc_u32 s21, s21, 0
	global_load_dwordx4 v[48:51], v195, s[20:21] nt
	s_add_u32 s20, s20, 0x5800
	s_addc_u32 s21, s21, 0
	global_load_dwordx4 v[52:55], v195, s[20:21] nt
	s_add_u32 s20, s20, 0x5800
	s_addc_u32 s21, s21, 0
	global_load_dwordx4 v[56:59], v195, s[20:21] nt
	s_add_u32 s20, s20, 0x5800
	s_addc_u32 s21, s21, 0
	global_load_dwordx4 v[60:63], v195, s[20:21] nt
	global_load_dwordx4 v[144:147], v199, s[36:37] offset:0
	global_load_dwordx4 v[148:151], v199, s[36:37] offset:16
	global_load_dwordx4 v[152:155], v199, s[36:37] offset:32
	global_load_dwordx4 v[156:159], v199, s[36:37] offset:48
	global_load_dwordx4 v[80:83], v195, s[22:23] nt
	s_add_u32 s22, s22, 0x5800
	s_addc_u32 s23, s23, 0
	global_load_dwordx4 v[84:87], v195, s[22:23] nt
	s_add_u32 s22, s22, 0x5800
	s_addc_u32 s23, s23, 0
	global_load_dwordx4 v[88:91], v195, s[22:23] nt
	s_add_u32 s22, s22, 0x5800
	s_addc_u32 s23, s23, 0
	global_load_dwordx4 v[92:95], v195, s[22:23] nt
	s_add_u32 s22, s22, 0x5800
	s_addc_u32 s23, s23, 0
	global_load_dwordx4 v[96:99], v195, s[22:23] nt
	s_add_u32 s22, s22, 0x5800
	s_addc_u32 s23, s23, 0
	global_load_dwordx4 v[100:103], v195, s[22:23] nt
	s_add_u32 s22, s22, 0x5800
	s_addc_u32 s23, s23, 0
	global_load_dwordx4 v[104:107], v195, s[22:23] nt
	s_add_u32 s22, s22, 0x5800
	s_addc_u32 s23, s23, 0
	global_load_dwordx4 v[108:111], v195, s[22:23] nt
	s_add_u32 s22, s22, 0x5800
	s_addc_u32 s23, s23, 0
	global_load_dwordx4 v[112:115], v195, s[22:23] nt
	s_add_u32 s22, s22, 0x5800
	s_addc_u32 s23, s23, 0
	global_load_dwordx4 v[116:119], v195, s[22:23] nt
	s_add_u32 s22, s22, 0x5800
	s_addc_u32 s23, s23, 0
	global_load_dwordx4 v[120:123], v195, s[22:23] nt
	s_add_u32 s22, s22, 0x5800
	s_addc_u32 s23, s23, 0
	global_load_dwordx4 v[124:127], v195, s[22:23] nt
	s_add_u32 s22, s22, 0x5800
	s_addc_u32 s23, s23, 0
	global_load_dwordx4 v[128:131], v195, s[22:23] nt
	s_add_u32 s22, s22, 0x5800
	s_addc_u32 s23, s23, 0
	global_load_dwordx4 v[132:135], v195, s[22:23] nt
	s_add_u32 s22, s22, 0x5800
	s_addc_u32 s23, s23, 0
	global_load_dwordx4 v[136:139], v195, s[22:23] nt
	s_add_u32 s22, s22, 0x5800
	s_addc_u32 s23, s23, 0
	global_load_dwordx4 v[140:143], v195, s[22:23] nt
.Lp4_copy_main:
	s_cmpk_lt_u32 s2, 0xc0
	s_cbranch_scc0 .Lp4_copy_two
	s_add_i32 s44, s2, 512
	s_cmpk_ge_u32 s44, 0x160
	s_cselect_b32 s45, 1, 0
	s_mul_i32 s67, s45, 0x160
	s_sub_i32 s44, s44, s67
	s_mul_i32 s67, s44, 2979
	s_lshr_b32 s67, s67, 16
	s_mul_i32 s69, s67, 22
	s_sub_i32 s69, s44, s69
	s_lshl_b32 s67, s67, 7
	s_cmp_eq_u32 s45, 0
	s_cselect_b32 s24, s60, s62
	s_cselect_b32 s25, s61, s63
	s_mul_i32 s76, s67, 0x5800
	s_lshl_b32 s44, s69, 10
	s_add_i32 s76, s76, s44
	s_lshl_b32 s44, s91, 7
	s_add_i32 s76, s76, s44
	s_add_u32 s24, s24, s76
	s_addc_u32 s25, s25, 0
	s_lshl_b32 s44, s67, 2
	s_add_u32 s38, s40, s44
	s_addc_u32 s39, s41, 0
	s_lshl_b32 s44, s69, 20
	s_lshl_b32 s45, s45, 18
	s_add_i32 s44, s44, s45
	s_add_i32 s44, s44, s67
	s_add_i32 s44, s44, s77
	s_add_u32 s30, s50, s44
	s_addc_u32 s31, s51, 0
	s_add_u32 s30, s30, 0x6300000
	s_addc_u32 s31, s31, 0
	s_waitcnt vmcnt(20)
	v_mul_f32_e32 v64, v64, v192
	v_mul_f32_e32 v65, v65, v192
	v_mul_f32_e32 v66, v66, v192
	v_mul_f32_e32 v67, v67, v192
	v_mul_f32_e32 v68, v68, v192
	v_mul_f32_e32 v69, v69, v192
	v_mul_f32_e32 v70, v70, v192
	v_mul_f32_e32 v71, v71, v192
	v_mul_f32_e32 v72, v72, v192
	v_mul_f32_e32 v73, v73, v192
	v_mul_f32_e32 v74, v74, v192
	v_mul_f32_e32 v75, v75, v192
	v_mul_f32_e32 v76, v76, v192
	v_mul_f32_e32 v77, v77, v192
	v_mul_f32_e32 v78, v78, v192
	v_mul_f32_e32 v79, v79, v192
	v_pk_mul_f32 v[0:1], v[0:1], v[64:65] op_sel_hi:[1,0]
	v_pk_mul_f32 v[2:3], v[2:3], v[64:65] op_sel_hi:[1,0]
	v_pk_mul_f32 v[4:5], v[4:5], v[64:65] op_sel:[0,1] op_sel_hi:[1,1]
	v_pk_mul_f32 v[6:7], v[6:7], v[64:65] op_sel:[0,1] op_sel_hi:[1,1]
	v_pk_mul_f32 v[8:9], v[8:9], v[66:67] op_sel_hi:[1,0]
	v_pk_mul_f32 v[10:11], v[10:11], v[66:67] op_sel_hi:[1,0]
	v_pk_mul_f32 v[12:13], v[12:13], v[66:67] op_sel:[0,1] op_sel_hi:[1,1]
	v_pk_mul_f32 v[14:15], v[14:15], v[66:67] op_sel:[0,1] op_sel_hi:[1,1]
	v_pk_mul_f32 v[16:17], v[16:17], v[68:69] op_sel_hi:[1,0]
	v_pk_mul_f32 v[18:19], v[18:19], v[68:69] op_sel_hi:[1,0]
	v_pk_mul_f32 v[20:21], v[20:21], v[68:69] op_sel:[0,1] op_sel_hi:[1,1]
	v_pk_mul_f32 v[22:23], v[22:23], v[68:69] op_sel:[0,1] op_sel_hi:[1,1]
	v_pk_mul_f32 v[24:25], v[24:25], v[70:71] op_sel_hi:[1,0]
	v_pk_mul_f32 v[26:27], v[26:27], v[70:71] op_sel_hi:[1,0]
	v_pk_mul_f32 v[28:29], v[28:29], v[70:71] op_sel:[0,1] op_sel_hi:[1,1]
	v_pk_mul_f32 v[30:31], v[30:31], v[70:71] op_sel:[0,1] op_sel_hi:[1,1]
	v_pk_mul_f32 v[32:33], v[32:33], v[72:73] op_sel_hi:[1,0]
	v_pk_mul_f32 v[34:35], v[34:35], v[72:73] op_sel_hi:[1,0]
	v_pk_mul_f32 v[36:37], v[36:37], v[72:73] op_sel:[0,1] op_sel_hi:[1,1]
	v_pk_mul_f32 v[38:39], v[38:39], v[72:73] op_sel:[0,1] op_sel_hi:[1,1]
	v_pk_mul_f32 v[40:41], v[40:41], v[74:75] op_sel_hi:[1,0]
	v_pk_mul_f32 v[42:43], v[42:43], v[74:75] op_sel_hi:[1,0]
	v_pk_mul_f32 v[44:45], v[44:45], v[74:75] op_sel:[0,1] op_sel_hi:[1,1]
	v_pk_mul_f32 v[46:47], v[46:47], v[74:75] op_sel:[0,1] op_sel_hi:[1,1]
	v_pk_mul_f32 v[48:49], v[48:49], v[76:77] op_sel_hi:[1,0]
	v_pk_mul_f32 v[50:51], v[50:51], v[76:77] op_sel_hi:[1,0]
	v_pk_mul_f32 v[52:53], v[52:53], v[76:77] op_sel:[0,1] op_sel_hi:[1,1]
	v_pk_mul_f32 v[54:55], v[54:55], v[76:77] op_sel:[0,1] op_sel_hi:[1,1]
	v_pk_mul_f32 v[56:57], v[56:57], v[78:79] op_sel_hi:[1,0]
	v_pk_mul_f32 v[58:59], v[58:59], v[78:79] op_sel_hi:[1,0]
	v_pk_mul_f32 v[60:61], v[60:61], v[78:79] op_sel:[0,1] op_sel_hi:[1,1]
	v_pk_mul_f32 v[62:63], v[62:63], v[78:79] op_sel:[0,1] op_sel_hi:[1,1]
	v_med3_f32 v0, v0, v194, v193
	v_med3_f32 v1, v1, v194, v193
	v_med3_f32 v2, v2, v194, v193
	v_med3_f32 v3, v3, v194, v193
	v_med3_f32 v4, v4, v194, v193
	v_med3_f32 v5, v5, v194, v193
	v_med3_f32 v6, v6, v194, v193
	v_med3_f32 v7, v7, v194, v193
	v_med3_f32 v8, v8, v194, v193
	v_med3_f32 v9, v9, v194, v193
	v_med3_f32 v10, v10, v194, v193
	v_med3_f32 v11, v11, v194, v193
	v_med3_f32 v12, v12, v194, v193
	v_med3_f32 v13, v13, v194, v193
	v_med3_f32 v14, v14, v194, v193
	v_med3_f32 v15, v15, v194, v193
	v_med3_f32 v16, v16, v194, v193
	v_med3_f32 v17, v17, v194, v193
	v_med3_f32 v18, v18, v194, v193
	v_med3_f32 v19, v19, v194, v193
	v_med3_f32 v20, v20, v194, v193
	v_med3_f32 v21, v21, v194, v193
	v_med3_f32 v22, v22, v194, v193
	v_med3_f32 v23, v23, v194, v193
	v_med3_f32 v24, v24, v194, v193
	v_med3_f32 v25, v25, v194, v193
	v_med3_f32 v26, v26, v194, v193
	v_med3_f32 v27, v27, v194, v193
	v_med3_f32 v28, v28, v194, v193
	v_med3_f32 v29, v29, v194, v193
	v_med3_f32 v30, v30, v194, v193
	v_med3_f32 v31, v31, v194, v193
	v_med3_f32 v32, v32, v194, v193
	v_med3_f32 v33, v33, v194, v193
	v_med3_f32 v34, v34, v194, v193
	v_med3_f32 v35, v35, v194, v193
	v_med3_f32 v36, v36, v194, v193
	v_med3_f32 v37, v37, v194, v193
	v_med3_f32 v38, v38, v194, v193
	v_med3_f32 v39, v39, v194, v193
	v_med3_f32 v40, v40, v194, v193
	v_med3_f32 v41, v41, v194, v193
	v_med3_f32 v42, v42, v194, v193
	v_med3_f32 v43, v43, v194, v193
	v_med3_f32 v44, v44, v194, v193
	v_med3_f32 v45, v45, v194, v193
	v_med3_f32 v46, v46, v194, v193
	v_med3_f32 v47, v47, v194, v193
	v_med3_f32 v48, v48, v194, v193
	v_med3_f32 v49, v49, v194, v193
	v_med3_f32 v50, v50, v194, v193
	v_med3_f32 v51, v51, v194, v193
	v_med3_f32 v52, v52, v194, v193
	v_med3_f32 v53, v53, v194, v193
	v_med3_f32 v54, v54, v194, v193
	v_med3_f32 v55, v55, v194, v193
	v_med3_f32 v56, v56, v194, v193
	v_med3_f32 v57, v57, v194, v193
	v_med3_f32 v58, v58, v194, v193
	v_med3_f32 v59, v59, v194, v193
	v_med3_f32 v60, v60, v194, v193
	v_med3_f32 v61, v61, v194, v193
	v_med3_f32 v62, v62, v194, v193
	v_med3_f32 v63, v63, v194, v193
	v_cvt_pk_fp8_f32 v160, v0, v4
	v_cvt_pk_fp8_f32 v161, v16, v20
	v_cvt_pk_fp8_f32 v162, v32, v36
	v_cvt_pk_fp8_f32 v163, v48, v52
	v_cvt_pk_fp8_f32 v164, v1, v5
	v_cvt_pk_fp8_f32 v165, v17, v21
	v_cvt_pk_fp8_f32 v166, v33, v37
	v_cvt_pk_fp8_f32 v167, v49, v53
	v_cvt_pk_fp8_f32 v168, v2, v6
	v_cvt_pk_fp8_f32 v169, v18, v22
	v_cvt_pk_fp8_f32 v170, v34, v38
	v_cvt_pk_fp8_f32 v171, v50, v54
	v_cvt_pk_fp8_f32 v172, v3, v7
	v_cvt_pk_fp8_f32 v173, v19, v23
	v_cvt_pk_fp8_f32 v174, v35, v39
	v_cvt_pk_fp8_f32 v175, v51, v55
	v_cvt_pk_fp8_f32 v160, v8, v12 op_sel:[0,0,1]
	v_cvt_pk_fp8_f32 v161, v24, v28 op_sel:[0,0,1]
	v_cvt_pk_fp8_f32 v162, v40, v44 op_sel:[0,0,1]
	v_cvt_pk_fp8_f32 v163, v56, v60 op_sel:[0,0,1]
	v_cvt_pk_fp8_f32 v164, v9, v13 op_sel:[0,0,1]
	v_cvt_pk_fp8_f32 v165, v25, v29 op_sel:[0,0,1]
	v_cvt_pk_fp8_f32 v166, v41, v45 op_sel:[0,0,1]
	v_cvt_pk_fp8_f32 v167, v57, v61 op_sel:[0,0,1]
	v_cvt_pk_fp8_f32 v168, v10, v14 op_sel:[0,0,1]
	v_cvt_pk_fp8_f32 v169, v26, v30 op_sel:[0,0,1]
	v_cvt_pk_fp8_f32 v170, v42, v46 op_sel:[0,0,1]
	v_cvt_pk_fp8_f32 v171, v58, v62 op_sel:[0,0,1]
	v_cvt_pk_fp8_f32 v172, v11, v15 op_sel:[0,0,1]
	v_cvt_pk_fp8_f32 v173, v27, v31 op_sel:[0,0,1]
	v_cvt_pk_fp8_f32 v174, v43, v47 op_sel:[0,0,1]
	v_cvt_pk_fp8_f32 v175, v59, v63 op_sel:[0,0,1]
	s_nop 0
	ds_bpermute_b32 v176, v198, v160
	ds_bpermute_b32 v177, v198, v161
	ds_bpermute_b32 v178, v198, v162
	ds_bpermute_b32 v179, v198, v163
	ds_bpermute_b32 v180, v198, v164
	ds_bpermute_b32 v181, v198, v165
	ds_bpermute_b32 v182, v198, v166
	ds_bpermute_b32 v183, v198, v167
	ds_bpermute_b32 v184, v198, v168
	ds_bpermute_b32 v185, v198, v169
	ds_bpermute_b32 v186, v198, v170
	ds_bpermute_b32 v187, v198, v171
	ds_bpermute_b32 v188, v198, v172
	ds_bpermute_b32 v189, v198, v173
	ds_bpermute_b32 v190, v198, v174
	ds_bpermute_b32 v191, v198, v175
	s_waitcnt lgkmcnt(0)
	global_store_dwordx4 v196, v[176:179], s[26:27]
	global_store_dwordx4 v196, v[180:183], s[26:27] offset:2048
	global_store_dwordx4 v197, v[184:187], s[26:27]
	global_store_dwordx4 v197, v[188:191], s[26:27] offset:2048
	global_load_dwordx4 v[64:67], v199, s[38:39] offset:0
	global_load_dwordx4 v[68:71], v199, s[38:39] offset:16
	global_load_dwordx4 v[72:75], v199, s[38:39] offset:32
	global_load_dwordx4 v[76:79], v199, s[38:39] offset:48
	global_load_dwordx4 v[0:3], v195, s[24:25] nt
	s_add_u32 s24, s24, 0x5800
	s_addc_u32 s25, s25, 0
	global_load_dwordx4 v[4:7], v195, s[24:25] nt
	s_add_u32 s24, s24, 0x5800
	s_addc_u32 s25, s25, 0
	global_load_dwordx4 v[8:11], v195, s[24:25] nt
	s_add_u32 s24, s24, 0x5800
	s_addc_u32 s25, s25, 0
	global_load_dwordx4 v[12:15], v195, s[24:25] nt
	s_add_u32 s24, s24, 0x5800
	s_addc_u32 s25, s25, 0
	global_load_dwordx4 v[16:19], v195, s[24:25] nt
	s_add_u32 s24, s24, 0x5800
	s_addc_u32 s25, s25, 0
	global_load_dwordx4 v[20:23], v195, s[24:25] nt
	s_add_u32 s24, s24, 0x5800
	s_addc_u32 s25, s25, 0
	global_load_dwordx4 v[24:27], v195, s[24:25] nt
	s_add_u32 s24, s24, 0x5800
	s_addc_u32 s25, s25, 0
	global_load_dwordx4 v[28:31], v195, s[24:25] nt
	s_add_u32 s24, s24, 0x5800
	s_addc_u32 s25, s25, 0
	global_load_dwordx4 v[32:35], v195, s[24:25] nt
	s_add_u32 s24, s24, 0x5800
	s_addc_u32 s25, s25, 0
	global_load_dwordx4 v[36:39], v195, s[24:25] nt
	s_add_u32 s24, s24, 0x5800
	s_addc_u32 s25, s25, 0
	global_load_dwordx4 v[40:43], v195, s[24:25] nt
	s_add_u32 s24, s24, 0x5800
	s_addc_u32 s25, s25, 0
	global_load_dwordx4 v[44:47], v195, s[24:25] nt
	s_add_u32 s24, s24, 0x5800
	s_addc_u32 s25, s25, 0
	global_load_dwordx4 v[48:51], v195, s[24:25] nt
	s_add_u32 s24, s24, 0x5800
	s_addc_u32 s25, s25, 0
	global_load_dwordx4 v[52:55], v195, s[24:25] nt
	s_add_u32 s24, s24, 0x5800
	s_addc_u32 s25, s25, 0
	global_load_dwordx4 v[56:59], v195, s[24:25] nt
	s_add_u32 s24, s24, 0x5800
	s_addc_u32 s25, s25, 0
	global_load_dwordx4 v[60:63], v195, s[24:25] nt
	s_waitcnt vmcnt(24)
	v_mul_f32_e32 v144, v144, v192
	v_mul_f32_e32 v145, v145, v192
	v_mul_f32_e32 v146, v146, v192
	v_mul_f32_e32 v147, v147, v192
	v_mul_f32_e32 v148, v148, v192
	v_mul_f32_e32 v149, v149, v192
	v_mul_f32_e32 v150, v150, v192
	v_mul_f32_e32 v151, v151, v192
	v_mul_f32_e32 v152, v152, v192
	v_mul_f32_e32 v153, v153, v192
	v_mul_f32_e32 v154, v154, v192
	v_mul_f32_e32 v155, v155, v192
	v_mul_f32_e32 v156, v156, v192
	v_mul_f32_e32 v157, v157, v192
	v_mul_f32_e32 v158, v158, v192
	v_mul_f32_e32 v159, v159, v192
	v_pk_mul_f32 v[80:81], v[80:81], v[144:145] op_sel_hi:[1,0]
	v_pk_mul_f32 v[82:83], v[82:83], v[144:145] op_sel_hi:[1,0]
	v_pk_mul_f32 v[84:85], v[84:85], v[144:145] op_sel:[0,1] op_sel_hi:[1,1]
	v_pk_mul_f32 v[86:87], v[86:87], v[144:145] op_sel:[0,1] op_sel_hi:[1,1]
	v_pk_mul_f32 v[88:89], v[88:89], v[146:147] op_sel_hi:[1,0]
	v_pk_mul_f32 v[90:91], v[90:91], v[146:147] op_sel_hi:[1,0]
	v_pk_mul_f32 v[92:93], v[92:93], v[146:147] op_sel:[0,1] op_sel_hi:[1,1]
	v_pk_mul_f32 v[94:95], v[94:95], v[146:147] op_sel:[0,1] op_sel_hi:[1,1]
	v_pk_mul_f32 v[96:97], v[96:97], v[148:149] op_sel_hi:[1,0]
	v_pk_mul_f32 v[98:99], v[98:99], v[148:149] op_sel_hi:[1,0]
	v_pk_mul_f32 v[100:101], v[100:101], v[148:149] op_sel:[0,1] op_sel_hi:[1,1]
	v_pk_mul_f32 v[102:103], v[102:103], v[148:149] op_sel:[0,1] op_sel_hi:[1,1]
	v_pk_mul_f32 v[104:105], v[104:105], v[150:151] op_sel_hi:[1,0]
	v_pk_mul_f32 v[106:107], v[106:107], v[150:151] op_sel_hi:[1,0]
	v_pk_mul_f32 v[108:109], v[108:109], v[150:151] op_sel:[0,1] op_sel_hi:[1,1]
	v_pk_mul_f32 v[110:111], v[110:111], v[150:151] op_sel:[0,1] op_sel_hi:[1,1]
	v_pk_mul_f32 v[112:113], v[112:113], v[152:153] op_sel_hi:[1,0]
	v_pk_mul_f32 v[114:115], v[114:115], v[152:153] op_sel_hi:[1,0]
	v_pk_mul_f32 v[116:117], v[116:117], v[152:153] op_sel:[0,1] op_sel_hi:[1,1]
	v_pk_mul_f32 v[118:119], v[118:119], v[152:153] op_sel:[0,1] op_sel_hi:[1,1]
	v_pk_mul_f32 v[120:121], v[120:121], v[154:155] op_sel_hi:[1,0]
	v_pk_mul_f32 v[122:123], v[122:123], v[154:155] op_sel_hi:[1,0]
	v_pk_mul_f32 v[124:125], v[124:125], v[154:155] op_sel:[0,1] op_sel_hi:[1,1]
	v_pk_mul_f32 v[126:127], v[126:127], v[154:155] op_sel:[0,1] op_sel_hi:[1,1]
	v_pk_mul_f32 v[128:129], v[128:129], v[156:157] op_sel_hi:[1,0]
	v_pk_mul_f32 v[130:131], v[130:131], v[156:157] op_sel_hi:[1,0]
	v_pk_mul_f32 v[132:133], v[132:133], v[156:157] op_sel:[0,1] op_sel_hi:[1,1]
	v_pk_mul_f32 v[134:135], v[134:135], v[156:157] op_sel:[0,1] op_sel_hi:[1,1]
	v_pk_mul_f32 v[136:137], v[136:137], v[158:159] op_sel_hi:[1,0]
	v_pk_mul_f32 v[138:139], v[138:139], v[158:159] op_sel_hi:[1,0]
	v_pk_mul_f32 v[140:141], v[140:141], v[158:159] op_sel:[0,1] op_sel_hi:[1,1]
	v_pk_mul_f32 v[142:143], v[142:143], v[158:159] op_sel:[0,1] op_sel_hi:[1,1]
	v_med3_f32 v80, v80, v194, v193
	v_med3_f32 v81, v81, v194, v193
	v_med3_f32 v82, v82, v194, v193
	v_med3_f32 v83, v83, v194, v193
	v_med3_f32 v84, v84, v194, v193
	v_med3_f32 v85, v85, v194, v193
	v_med3_f32 v86, v86, v194, v193
	v_med3_f32 v87, v87, v194, v193
	v_med3_f32 v88, v88, v194, v193
	v_med3_f32 v89, v89, v194, v193
	v_med3_f32 v90, v90, v194, v193
	v_med3_f32 v91, v91, v194, v193
	v_med3_f32 v92, v92, v194, v193
	v_med3_f32 v93, v93, v194, v193
	v_med3_f32 v94, v94, v194, v193
	v_med3_f32 v95, v95, v194, v193
	v_med3_f32 v96, v96, v194, v193
	v_med3_f32 v97, v97, v194, v193
	v_med3_f32 v98, v98, v194, v193
	v_med3_f32 v99, v99, v194, v193
	v_med3_f32 v100, v100, v194, v193
	v_med3_f32 v101, v101, v194, v193
	v_med3_f32 v102, v102, v194, v193
	v_med3_f32 v103, v103, v194, v193
	v_med3_f32 v104, v104, v194, v193
	v_med3_f32 v105, v105, v194, v193
	v_med3_f32 v106, v106, v194, v193
	v_med3_f32 v107, v107, v194, v193
	v_med3_f32 v108, v108, v194, v193
	v_med3_f32 v109, v109, v194, v193
	v_med3_f32 v110, v110, v194, v193
	v_med3_f32 v111, v111, v194, v193
	v_med3_f32 v112, v112, v194, v193
	v_med3_f32 v113, v113, v194, v193
	v_med3_f32 v114, v114, v194, v193
	v_med3_f32 v115, v115, v194, v193
	v_med3_f32 v116, v116, v194, v193
	v_med3_f32 v117, v117, v194, v193
	v_med3_f32 v118, v118, v194, v193
	v_med3_f32 v119, v119, v194, v193
	v_med3_f32 v120, v120, v194, v193
	v_med3_f32 v121, v121, v194, v193
	v_med3_f32 v122, v122, v194, v193
	v_med3_f32 v123, v123, v194, v193
	v_med3_f32 v124, v124, v194, v193
	v_med3_f32 v125, v125, v194, v193
	v_med3_f32 v126, v126, v194, v193
	v_med3_f32 v127, v127, v194, v193
	v_med3_f32 v128, v128, v194, v193
	v_med3_f32 v129, v129, v194, v193
	v_med3_f32 v130, v130, v194, v193
	v_med3_f32 v131, v131, v194, v193
	v_med3_f32 v132, v132, v194, v193
	v_med3_f32 v133, v133, v194, v193
	v_med3_f32 v134, v134, v194, v193
	v_med3_f32 v135, v135, v194, v193
	v_med3_f32 v136, v136, v194, v193
	v_med3_f32 v137, v137, v194, v193
	v_med3_f32 v138, v138, v194, v193
	v_med3_f32 v139, v139, v194, v193
	v_med3_f32 v140, v140, v194, v193
	v_med3_f32 v141, v141, v194, v193
	v_med3_f32 v142, v142, v194, v193
	v_med3_f32 v143, v143, v194, v193
	v_cvt_pk_fp8_f32 v160, v80, v84
	v_cvt_pk_fp8_f32 v161, v96, v100
	v_cvt_pk_fp8_f32 v162, v112, v116
	v_cvt_pk_fp8_f32 v163, v128, v132
	v_cvt_pk_fp8_f32 v164, v81, v85
	v_cvt_pk_fp8_f32 v165, v97, v101
	v_cvt_pk_fp8_f32 v166, v113, v117
	v_cvt_pk_fp8_f32 v167, v129, v133
	v_cvt_pk_fp8_f32 v168, v82, v86
	v_cvt_pk_fp8_f32 v169, v98, v102
	v_cvt_pk_fp8_f32 v170, v114, v118
	v_cvt_pk_fp8_f32 v171, v130, v134
	v_cvt_pk_fp8_f32 v172, v83, v87
	v_cvt_pk_fp8_f32 v173, v99, v103
	v_cvt_pk_fp8_f32 v174, v115, v119
	v_cvt_pk_fp8_f32 v175, v131, v135
	v_cvt_pk_fp8_f32 v160, v88, v92 op_sel:[0,0,1]
	v_cvt_pk_fp8_f32 v161, v104, v108 op_sel:[0,0,1]
	v_cvt_pk_fp8_f32 v162, v120, v124 op_sel:[0,0,1]
	v_cvt_pk_fp8_f32 v163, v136, v140 op_sel:[0,0,1]
	v_cvt_pk_fp8_f32 v164, v89, v93 op_sel:[0,0,1]
	v_cvt_pk_fp8_f32 v165, v105, v109 op_sel:[0,0,1]
	v_cvt_pk_fp8_f32 v166, v121, v125 op_sel:[0,0,1]
	v_cvt_pk_fp8_f32 v167, v137, v141 op_sel:[0,0,1]
	v_cvt_pk_fp8_f32 v168, v90, v94 op_sel:[0,0,1]
	v_cvt_pk_fp8_f32 v169, v106, v110 op_sel:[0,0,1]
	v_cvt_pk_fp8_f32 v170, v122, v126 op_sel:[0,0,1]
	v_cvt_pk_fp8_f32 v171, v138, v142 op_sel:[0,0,1]
	v_cvt_pk_fp8_f32 v172, v91, v95 op_sel:[0,0,1]
	v_cvt_pk_fp8_f32 v173, v107, v111 op_sel:[0,0,1]
	v_cvt_pk_fp8_f32 v174, v123, v127 op_sel:[0,0,1]
	v_cvt_pk_fp8_f32 v175, v139, v143 op_sel:[0,0,1]
	s_nop 0
	ds_bpermute_b32 v176, v198, v160
	ds_bpermute_b32 v177, v198, v161
	ds_bpermute_b32 v178, v198, v162
	ds_bpermute_b32 v179, v198, v163
	ds_bpermute_b32 v180, v198, v164
	ds_bpermute_b32 v181, v198, v165
	ds_bpermute_b32 v182, v198, v166
	ds_bpermute_b32 v183, v198, v167
	ds_bpermute_b32 v184, v198, v168
	ds_bpermute_b32 v185, v198, v169
	ds_bpermute_b32 v186, v198, v170
	ds_bpermute_b32 v187, v198, v171
	ds_bpermute_b32 v188, v198, v172
	ds_bpermute_b32 v189, v198, v173
	ds_bpermute_b32 v190, v198, v174
	ds_bpermute_b32 v191, v198, v175
	s_waitcnt lgkmcnt(0)
	global_store_dwordx4 v196, v[176:179], s[28:29]
	global_store_dwordx4 v196, v[180:183], s[28:29] offset:2048
	global_store_dwordx4 v197, v[184:187], s[28:29]
	global_store_dwordx4 v197, v[188:191], s[28:29] offset:2048
	s_waitcnt vmcnt(4)
	v_mul_f32_e32 v64, v64, v192
	v_mul_f32_e32 v65, v65, v192
	v_mul_f32_e32 v66, v66, v192
	v_mul_f32_e32 v67, v67, v192
	v_mul_f32_e32 v68, v68, v192
	v_mul_f32_e32 v69, v69, v192
	v_mul_f32_e32 v70, v70, v192
	v_mul_f32_e32 v71, v71, v192
	v_mul_f32_e32 v72, v72, v192
	v_mul_f32_e32 v73, v73, v192
	v_mul_f32_e32 v74, v74, v192
	v_mul_f32_e32 v75, v75, v192
	v_mul_f32_e32 v76, v76, v192
	v_mul_f32_e32 v77, v77, v192
	v_mul_f32_e32 v78, v78, v192
	v_mul_f32_e32 v79, v79, v192
	v_pk_mul_f32 v[0:1], v[0:1], v[64:65] op_sel_hi:[1,0]
	v_pk_mul_f32 v[2:3], v[2:3], v[64:65] op_sel_hi:[1,0]
	v_pk_mul_f32 v[4:5], v[4:5], v[64:65] op_sel:[0,1] op_sel_hi:[1,1]
	v_pk_mul_f32 v[6:7], v[6:7], v[64:65] op_sel:[0,1] op_sel_hi:[1,1]
	v_pk_mul_f32 v[8:9], v[8:9], v[66:67] op_sel_hi:[1,0]
	v_pk_mul_f32 v[10:11], v[10:11], v[66:67] op_sel_hi:[1,0]
	v_pk_mul_f32 v[12:13], v[12:13], v[66:67] op_sel:[0,1] op_sel_hi:[1,1]
	v_pk_mul_f32 v[14:15], v[14:15], v[66:67] op_sel:[0,1] op_sel_hi:[1,1]
	v_pk_mul_f32 v[16:17], v[16:17], v[68:69] op_sel_hi:[1,0]
	v_pk_mul_f32 v[18:19], v[18:19], v[68:69] op_sel_hi:[1,0]
	v_pk_mul_f32 v[20:21], v[20:21], v[68:69] op_sel:[0,1] op_sel_hi:[1,1]
	v_pk_mul_f32 v[22:23], v[22:23], v[68:69] op_sel:[0,1] op_sel_hi:[1,1]
	v_pk_mul_f32 v[24:25], v[24:25], v[70:71] op_sel_hi:[1,0]
	v_pk_mul_f32 v[26:27], v[26:27], v[70:71] op_sel_hi:[1,0]
	v_pk_mul_f32 v[28:29], v[28:29], v[70:71] op_sel:[0,1] op_sel_hi:[1,1]
	v_pk_mul_f32 v[30:31], v[30:31], v[70:71] op_sel:[0,1] op_sel_hi:[1,1]
	v_pk_mul_f32 v[32:33], v[32:33], v[72:73] op_sel_hi:[1,0]
	v_pk_mul_f32 v[34:35], v[34:35], v[72:73] op_sel_hi:[1,0]
	v_pk_mul_f32 v[36:37], v[36:37], v[72:73] op_sel:[0,1] op_sel_hi:[1,1]
	v_pk_mul_f32 v[38:39], v[38:39], v[72:73] op_sel:[0,1] op_sel_hi:[1,1]
	v_pk_mul_f32 v[40:41], v[40:41], v[74:75] op_sel_hi:[1,0]
	v_pk_mul_f32 v[42:43], v[42:43], v[74:75] op_sel_hi:[1,0]
	v_pk_mul_f32 v[44:45], v[44:45], v[74:75] op_sel:[0,1] op_sel_hi:[1,1]
	v_pk_mul_f32 v[46:47], v[46:47], v[74:75] op_sel:[0,1] op_sel_hi:[1,1]
	v_pk_mul_f32 v[48:49], v[48:49], v[76:77] op_sel_hi:[1,0]
	v_pk_mul_f32 v[50:51], v[50:51], v[76:77] op_sel_hi:[1,0]
	v_pk_mul_f32 v[52:53], v[52:53], v[76:77] op_sel:[0,1] op_sel_hi:[1,1]
	v_pk_mul_f32 v[54:55], v[54:55], v[76:77] op_sel:[0,1] op_sel_hi:[1,1]
	v_pk_mul_f32 v[56:57], v[56:57], v[78:79] op_sel_hi:[1,0]
	v_pk_mul_f32 v[58:59], v[58:59], v[78:79] op_sel_hi:[1,0]
	v_pk_mul_f32 v[60:61], v[60:61], v[78:79] op_sel:[0,1] op_sel_hi:[1,1]
	v_pk_mul_f32 v[62:63], v[62:63], v[78:79] op_sel:[0,1] op_sel_hi:[1,1]
	v_med3_f32 v0, v0, v194, v193
	v_med3_f32 v1, v1, v194, v193
	v_med3_f32 v2, v2, v194, v193
	v_med3_f32 v3, v3, v194, v193
	v_med3_f32 v4, v4, v194, v193
	v_med3_f32 v5, v5, v194, v193
	v_med3_f32 v6, v6, v194, v193
	v_med3_f32 v7, v7, v194, v193
	v_med3_f32 v8, v8, v194, v193
	v_med3_f32 v9, v9, v194, v193
	v_med3_f32 v10, v10, v194, v193
	v_med3_f32 v11, v11, v194, v193
	v_med3_f32 v12, v12, v194, v193
	v_med3_f32 v13, v13, v194, v193
	v_med3_f32 v14, v14, v194, v193
	v_med3_f32 v15, v15, v194, v193
	v_med3_f32 v16, v16, v194, v193
	v_med3_f32 v17, v17, v194, v193
	v_med3_f32 v18, v18, v194, v193
	v_med3_f32 v19, v19, v194, v193
	v_med3_f32 v20, v20, v194, v193
	v_med3_f32 v21, v21, v194, v193
	v_med3_f32 v22, v22, v194, v193
	v_med3_f32 v23, v23, v194, v193
	v_med3_f32 v24, v24, v194, v193
	v_med3_f32 v25, v25, v194, v193
	v_med3_f32 v26, v26, v194, v193
	v_med3_f32 v27, v27, v194, v193
	v_med3_f32 v28, v28, v194, v193
	v_med3_f32 v29, v29, v194, v193
	v_med3_f32 v30, v30, v194, v193
	v_med3_f32 v31, v31, v194, v193
	v_med3_f32 v32, v32, v194, v193
	v_med3_f32 v33, v33, v194, v193
	v_med3_f32 v34, v34, v194, v193
	v_med3_f32 v35, v35, v194, v193
	v_med3_f32 v36, v36, v194, v193
	v_med3_f32 v37, v37, v194, v193
	v_med3_f32 v38, v38, v194, v193
	v_med3_f32 v39, v39, v194, v193
	v_med3_f32 v40, v40, v194, v193
	v_med3_f32 v41, v41, v194, v193
	v_med3_f32 v42, v42, v194, v193
	v_med3_f32 v43, v43, v194, v193
	v_med3_f32 v44, v44, v194, v193
	v_med3_f32 v45, v45, v194, v193
	v_med3_f32 v46, v46, v194, v193
	v_med3_f32 v47, v47, v194, v193
	v_med3_f32 v48, v48, v194, v193
	v_med3_f32 v49, v49, v194, v193
	v_med3_f32 v50, v50, v194, v193
	v_med3_f32 v51, v51, v194, v193
	v_med3_f32 v52, v52, v194, v193
	v_med3_f32 v53, v53, v194, v193
	v_med3_f32 v54, v54, v194, v193
	v_med3_f32 v55, v55, v194, v193
	v_med3_f32 v56, v56, v194, v193
	v_med3_f32 v57, v57, v194, v193
	v_med3_f32 v58, v58, v194, v193
	v_med3_f32 v59, v59, v194, v193
	v_med3_f32 v60, v60, v194, v193
	v_med3_f32 v61, v61, v194, v193
	v_med3_f32 v62, v62, v194, v193
	v_med3_f32 v63, v63, v194, v193
	v_cvt_pk_fp8_f32 v160, v0, v4
	v_cvt_pk_fp8_f32 v161, v16, v20
	v_cvt_pk_fp8_f32 v162, v32, v36
	v_cvt_pk_fp8_f32 v163, v48, v52
	v_cvt_pk_fp8_f32 v164, v1, v5
	v_cvt_pk_fp8_f32 v165, v17, v21
	v_cvt_pk_fp8_f32 v166, v33, v37
	v_cvt_pk_fp8_f32 v167, v49, v53
	v_cvt_pk_fp8_f32 v168, v2, v6
	v_cvt_pk_fp8_f32 v169, v18, v22
	v_cvt_pk_fp8_f32 v170, v34, v38
	v_cvt_pk_fp8_f32 v171, v50, v54
	v_cvt_pk_fp8_f32 v172, v3, v7
	v_cvt_pk_fp8_f32 v173, v19, v23
	v_cvt_pk_fp8_f32 v174, v35, v39
	v_cvt_pk_fp8_f32 v175, v51, v55
	v_cvt_pk_fp8_f32 v160, v8, v12 op_sel:[0,0,1]
	v_cvt_pk_fp8_f32 v161, v24, v28 op_sel:[0,0,1]
	v_cvt_pk_fp8_f32 v162, v40, v44 op_sel:[0,0,1]
	v_cvt_pk_fp8_f32 v163, v56, v60 op_sel:[0,0,1]
	v_cvt_pk_fp8_f32 v164, v9, v13 op_sel:[0,0,1]
	v_cvt_pk_fp8_f32 v165, v25, v29 op_sel:[0,0,1]
	v_cvt_pk_fp8_f32 v166, v41, v45 op_sel:[0,0,1]
	v_cvt_pk_fp8_f32 v167, v57, v61 op_sel:[0,0,1]
	v_cvt_pk_fp8_f32 v168, v10, v14 op_sel:[0,0,1]
	v_cvt_pk_fp8_f32 v169, v26, v30 op_sel:[0,0,1]
	v_cvt_pk_fp8_f32 v170, v42, v46 op_sel:[0,0,1]
	v_cvt_pk_fp8_f32 v171, v58, v62 op_sel:[0,0,1]
	v_cvt_pk_fp8_f32 v172, v11, v15 op_sel:[0,0,1]
	v_cvt_pk_fp8_f32 v173, v27, v31 op_sel:[0,0,1]
	v_cvt_pk_fp8_f32 v174, v43, v47 op_sel:[0,0,1]
	v_cvt_pk_fp8_f32 v175, v59, v63 op_sel:[0,0,1]
	s_nop 0
	ds_bpermute_b32 v176, v198, v160
	ds_bpermute_b32 v177, v198, v161
	ds_bpermute_b32 v178, v198, v162
	ds_bpermute_b32 v179, v198, v163
	ds_bpermute_b32 v180, v198, v164
	ds_bpermute_b32 v181, v198, v165
	ds_bpermute_b32 v182, v198, v166
	ds_bpermute_b32 v183, v198, v167
	ds_bpermute_b32 v184, v198, v168
	ds_bpermute_b32 v185, v198, v169
	ds_bpermute_b32 v186, v198, v170
	ds_bpermute_b32 v187, v198, v171
	ds_bpermute_b32 v188, v198, v172
	ds_bpermute_b32 v189, v198, v173
	ds_bpermute_b32 v190, v198, v174
	ds_bpermute_b32 v191, v198, v175
	s_waitcnt lgkmcnt(0)
	global_store_dwordx4 v196, v[176:179], s[30:31]
	global_store_dwordx4 v196, v[180:183], s[30:31] offset:2048
	global_store_dwordx4 v197, v[184:187], s[30:31]
	global_store_dwordx4 v197, v[188:191], s[30:31] offset:2048
	s_branch .Lp4_copy_done

	.amdhsa_kernel _Z6mk_fwd4Args
		.amdhsa_group_segment_fixed_size 0
		.amdhsa_private_segment_fixed_size 0
		.amdhsa_kernarg_size 448
		.amdhsa_user_sgpr_count 2
		.amdhsa_user_sgpr_dispatch_ptr 0
		.amdhsa_user_sgpr_queue_ptr 0
		.amdhsa_user_sgpr_kernarg_segment_ptr 1
		.amdhsa_user_sgpr_dispatch_id 0
		.amdhsa_user_sgpr_kernarg_preload_length 0
		.amdhsa_user_sgpr_kernarg_preload_offset 0
		.amdhsa_user_sgpr_private_segment_size 0
		.amdhsa_uses_dynamic_stack 0
		.amdhsa_enable_private_segment 0
		.amdhsa_system_sgpr_workgroup_id_x 1
		.amdhsa_system_sgpr_workgroup_id_y 0
		.amdhsa_system_sgpr_workgroup_id_z 0
		.amdhsa_system_sgpr_workgroup_info 0
		.amdhsa_system_vgpr_workitem_id 2
		.amdhsa_next_free_vgpr 256
		.amdhsa_next_free_sgpr 102
		.amdhsa_accum_offset 256
		.amdhsa_reserve_vcc 1
		.amdhsa_float_round_mode_32 0
		.amdhsa_float_round_mode_16_64 0
		.amdhsa_float_denorm_mode_32 3
		.amdhsa_float_denorm_mode_16_64 3
		.amdhsa_dx10_clamp 1
		.amdhsa_ieee_mode 1
		.amdhsa_fp16_overflow 0
		.amdhsa_tg_split 0
		.amdhsa_exception_fp_ieee_invalid_op 0
		.amdhsa_exception_fp_denorm_src 0
		.amdhsa_exception_fp_ieee_div_zero 0
		.amdhsa_exception_fp_ieee_overflow 0
		.amdhsa_exception_fp_ieee_underflow 0
		.amdhsa_exception_fp_ieee_inexact 0
		.amdhsa_exception_int_div_zero 0
	.end_amdhsa_kernel
